# k16 with SwiGLU epilogue instruction stream software-pipelined across row groups: exp/rcp alternate with independent plain VALU (same math)
# baseline (speedup 1.0000x reference)
; __device__ __forceinline__ unsigned cvtpk(float lo, float hi) { f32x2_t v = {lo, hi}; bf16x2_t b = __builtin_convertvector(v, bf16x2_t); return __builtin_bit_cast(unsigned, b); }
;     __device__ __forceinline__ void operator()(const f32x4 (&acc)[2][2][4][2], const Unit& u, int wr, int wc, int fr, int fq) const {
;         const int row0 = u.pm * BM + wr * 64 + fr, col0 = u.pn * 128 + wc * 32 + 8 * fq;
; #pragma unroll
;         for (int ai = 0; ai < 2; ++ai)
; #pragma unroll
;             for (int m = 0; m < 4; ++m) {
;                 const int row = row0 + ai * HALF + m * 16;
;                 const float rs = 1.0f / sqrtf(ssq_sum(ssq + (size_t)row * 16) * (1.0f / DM) + EPS);
;                 float hv[8];
; #pragma unroll
;                 for (int n = 0; n < 2; ++n)
; #pragma unroll
;                     for (int e = 0; e < 4; ++e) {
;                         const float gg = acc[ai][0][m][n][e] * rs, uu = acc[ai][1][m][n][e] * rs;
;                         const float den = 1.0f + __builtin_amdgcn_exp2f(-gg * LOG2E);
;                         hv[n * 4 + e] = gg * uu * __builtin_amdgcn_rcpf(den);
;                     }
;                 u32x4 w; w.x = cvtpk(hv[0], hv[1]); w.y = cvtpk(hv[2], hv[3]); w.z = cvtpk(hv[4], hv[5]); w.w = cvtpk(hv[6], hv[7]);
;                 *(u32x4*)(H + (size_t)row * DFF + col0) = w;
;             }
.LBB0_244:
	v_readlane_b32 s9, v254, 7
	v_mbcnt_lo_u32_b32 v144, -1, 0
	v_mbcnt_hi_u32_b32 v144, -1, v144
	v_lshrrev_b32_e32 v145, 1, v144
	v_lshl_add_u32 v145, s9, 5, v145
	v_and_b32_e32 v146, 1, v144
	v_lshl_add_u32 v147, s8, 8, v145
	v_lshlrev_b32_e32 v147, 6, v147
	v_lshl_add_u32 v147, v146, 5, v147
	global_load_dwordx4 v[160:163], v147, s[14:15]
	global_load_dwordx4 v[164:167], v147, s[14:15] offset:16
	v_lshl_add_u32 v148, s8, 8, v152
	v_mov_b64_e32 v[146:147], s[16:17]
	v_mad_i64_i32 v[176:177], s[8:9], v148, s56, v[146:147]
	v_lshl_or_b32 v150, s2, 7, v154
	v_mov_b32_e32 v151, 0
	v_lshlrev_b64 v[150:151], 1, v[150:151]
	v_lshl_add_u64 v[176:177], v[176:177], 0, v[150:151]
	v_lshlrev_b32_e32 v145, 3, v145
	v_add_u32_e32 v145, 0x20100, v145
	v_lshlrev_b32_e32 v146, 3, v152
	v_add_u32_e32 v146, 0x20100, v146
	s_mov_b32 s9, 0
	s_waitcnt vmcnt(0)
	v_pk_add_f32 v[160:161], v[160:161], v[162:163]
	v_pk_add_f32 v[164:165], v[164:165], v[166:167]
	v_pk_add_f32 v[160:161], v[160:161], v[164:165]
	v_add_f32_e32 v160, v160, v161
	s_nop 1
	v_add_f32_dpp v160, v160, v160 quad_perm:[1,0,3,2] row_mask:0xf bank_mask:0xf
	v_fmamk_f32 v160, v160, 0x3a800000, v158
	v_rsq_f32_e32 v161, v160
	s_nop 0
	v_mul_f32_e32 v161, 0xbfb8aa3b, v161
	ds_write_b64 v145, v[160:161]
	s_waitcnt lgkmcnt(0)
	s_barrier
	ds_read_b64 v[160:161], v146 offset:0
	ds_read_b64 v[162:163], v146 offset:128
	ds_read_b64 v[164:165], v146 offset:256
	ds_read_b64 v[166:167], v146 offset:384
	ds_read_b64 v[168:169], v146 offset:1024
	ds_read_b64 v[170:171], v146 offset:1152
	ds_read_b64 v[172:173], v146 offset:1280
	ds_read_b64 v[174:175], v146 offset:1408
	v_pk_mul_f32 v[116:117], v[124:125], v[116:117]
	v_pk_mul_f32 v[118:119], v[126:127], v[118:119]
	v_pk_mul_f32 v[112:113], v[120:121], v[112:113]
	v_pk_mul_f32 v[114:115], v[122:123], v[114:115]
	s_waitcnt lgkmcnt(7)
	v_mov_b32_e32 v150, v161
	v_pk_mul_f32 v[124:125], v[124:125], v[150:151] op_sel_hi:[1,0]
	v_pk_mul_f32 v[126:127], v[126:127], v[150:151] op_sel_hi:[1,0]
	v_pk_mul_f32 v[120:121], v[120:121], v[150:151] op_sel_hi:[1,0]
	v_pk_mul_f32 v[122:123], v[122:123], v[150:151] op_sel_hi:[1,0]
	v_exp_f32_e32 v124, v124
	v_pk_mul_f32 v[100:101], v[108:109], v[100:101]
	v_fma_f32 v124, v124, v160, v160
	v_exp_f32_e32 v125, v125
	v_pk_mul_f32 v[102:103], v[110:111], v[102:103]
	v_fma_f32 v125, v125, v160, v160
	v_exp_f32_e32 v126, v126
	v_pk_mul_f32 v[96:97], v[104:105], v[96:97]
	v_fma_f32 v126, v126, v160, v160
	v_exp_f32_e32 v127, v127
	v_pk_mul_f32 v[98:99], v[106:107], v[98:99]
	v_fma_f32 v127, v127, v160, v160
	v_exp_f32_e32 v120, v120
	s_waitcnt lgkmcnt(6)
	v_fma_f32 v120, v120, v160, v160
	v_exp_f32_e32 v121, v121
	v_mov_b32_e32 v150, v163
	v_fma_f32 v121, v121, v160, v160
	v_exp_f32_e32 v122, v122
	v_pk_mul_f32 v[108:109], v[108:109], v[150:151] op_sel_hi:[1,0]
	v_fma_f32 v122, v122, v160, v160
	v_exp_f32_e32 v123, v123
	v_pk_mul_f32 v[110:111], v[110:111], v[150:151] op_sel_hi:[1,0]
	v_fma_f32 v123, v123, v160, v160
	v_rcp_f32_e32 v124, v124
	v_pk_mul_f32 v[104:105], v[104:105], v[150:151] op_sel_hi:[1,0]
	v_pk_mul_f32 v[106:107], v[106:107], v[150:151] op_sel_hi:[1,0]
	v_rcp_f32_e32 v125, v125
	v_rcp_f32_e32 v126, v126
	v_rcp_f32_e32 v127, v127
	v_rcp_f32_e32 v120, v120
	v_rcp_f32_e32 v121, v121
	v_rcp_f32_e32 v122, v122
	v_rcp_f32_e32 v123, v123
	v_exp_f32_e32 v108, v108
	v_pk_mul_f32 v[116:117], v[116:117], v[124:125]
	v_fma_f32 v108, v108, v162, v162
	v_exp_f32_e32 v109, v109
	v_pk_mul_f32 v[118:119], v[118:119], v[126:127]
	v_fma_f32 v109, v109, v162, v162
	v_exp_f32_e32 v110, v110
	v_pk_mul_f32 v[112:113], v[112:113], v[120:121]
	v_fma_f32 v110, v110, v162, v162
	v_exp_f32_e32 v111, v111
	v_pk_mul_f32 v[114:115], v[114:115], v[122:123]
	v_fma_f32 v111, v111, v162, v162
	v_exp_f32_e32 v104, v104
	v_cvt_pk_bf16_f32 v124, v116, v117
	v_fma_f32 v104, v104, v162, v162
	v_exp_f32_e32 v105, v105
	v_cvt_pk_bf16_f32 v125, v118, v119
	v_fma_f32 v105, v105, v162, v162
	v_exp_f32_e32 v106, v106
	v_cvt_pk_bf16_f32 v126, v112, v113
	v_fma_f32 v106, v106, v162, v162
	v_exp_f32_e32 v107, v107
	v_cvt_pk_bf16_f32 v127, v114, v115
	v_fma_f32 v107, v107, v162, v162
	v_rcp_f32_e32 v108, v108
	global_store_dwordx4 v[176:177], v[124:127], off
	v_pk_mul_f32 v[84:85], v[92:93], v[84:85]
	v_rcp_f32_e32 v109, v109
	v_pk_mul_f32 v[86:87], v[94:95], v[86:87]
	v_pk_mul_f32 v[80:81], v[88:89], v[80:81]
	v_rcp_f32_e32 v110, v110
	v_pk_mul_f32 v[82:83], v[90:91], v[82:83]
	s_waitcnt lgkmcnt(5)
	v_rcp_f32_e32 v111, v111
	v_mov_b32_e32 v150, v165
	v_pk_mul_f32 v[92:93], v[92:93], v[150:151] op_sel_hi:[1,0]
	v_rcp_f32_e32 v104, v104
	v_pk_mul_f32 v[94:95], v[94:95], v[150:151] op_sel_hi:[1,0]
	v_pk_mul_f32 v[88:89], v[88:89], v[150:151] op_sel_hi:[1,0]
	v_rcp_f32_e32 v105, v105
	v_pk_mul_f32 v[90:91], v[90:91], v[150:151] op_sel_hi:[1,0]
	v_rcp_f32_e32 v106, v106
	v_rcp_f32_e32 v107, v107
	v_exp_f32_e32 v92, v92
	s_mov_b32 s8, 0x16000
	v_fma_f32 v92, v92, v164, v164
	v_exp_f32_e32 v93, v93
	v_pk_mul_f32 v[100:101], v[100:101], v[108:109]
	v_fma_f32 v93, v93, v164, v164
	v_exp_f32_e32 v94, v94
	v_pk_mul_f32 v[102:103], v[102:103], v[110:111]
	v_fma_f32 v94, v94, v164, v164
	v_exp_f32_e32 v95, v95
	v_pk_mul_f32 v[96:97], v[96:97], v[104:105]
	v_fma_f32 v95, v95, v164, v164
	v_exp_f32_e32 v88, v88
	v_pk_mul_f32 v[98:99], v[98:99], v[106:107]
	v_fma_f32 v88, v88, v164, v164
	v_exp_f32_e32 v89, v89
	v_cvt_pk_bf16_f32 v108, v100, v101
	v_fma_f32 v89, v89, v164, v164
	v_exp_f32_e32 v90, v90
	v_cvt_pk_bf16_f32 v109, v102, v103
	v_fma_f32 v90, v90, v164, v164
	v_exp_f32_e32 v91, v91
	v_cvt_pk_bf16_f32 v110, v96, v97
	v_fma_f32 v91, v91, v164, v164
	v_rcp_f32_e32 v92, v92
	v_cvt_pk_bf16_f32 v111, v98, v99
	v_lshl_add_u64 v[178:179], v[176:177], 0, s[8:9]
	v_rcp_f32_e32 v93, v93
	global_store_dwordx4 v[178:179], v[108:111], off
	v_pk_mul_f32 v[68:69], v[76:77], v[68:69]
	v_rcp_f32_e32 v94, v94
	v_pk_mul_f32 v[70:71], v[78:79], v[70:71]
	v_pk_mul_f32 v[64:65], v[72:73], v[64:65]
	v_rcp_f32_e32 v95, v95
	v_pk_mul_f32 v[66:67], v[74:75], v[66:67]
	s_waitcnt lgkmcnt(4)
; __device__ __forceinline__ unsigned cvtpk(float lo, float hi) { f32x2_t v = {lo, hi}; bf16x2_t b = __builtin_convertvector(v, bf16x2_t); return __builtin_bit_cast(unsigned, b); }
;     __device__ __forceinline__ void operator()(const f32x4 (&acc)[2][2][4][2], const Unit& u, int wr, int wc, int fr, int fq) const {
;     ...
;             for (int m = 0; m < 4; ++m) {
;                 const int row = row0 + ai * HALF + m * 16;
;                 const float rs = 1.0f / sqrtf(ssq_sum(ssq + (size_t)row * 16) * (1.0f / DM) + EPS);
;                 float hv[8];
; #pragma unroll
;                 for (int n = 0; n < 2; ++n)
; #pragma unroll
;                     for (int e = 0; e < 4; ++e) {
;                         const float gg = acc[ai][0][m][n][e] * rs, uu = acc[ai][1][m][n][e] * rs;
;                         const float den = 1.0f + __builtin_amdgcn_exp2f(-gg * LOG2E);
;                         hv[n * 4 + e] = gg * uu * __builtin_amdgcn_rcpf(den);
;                     }
;                 u32x4 w; w.x = cvtpk(hv[0], hv[1]); w.y = cvtpk(hv[2], hv[3]); w.z = cvtpk(hv[4], hv[5]); w.w = cvtpk(hv[6], hv[7]);
;                 *(u32x4*)(H + (size_t)row * DFF + col0) = w;
	v_rcp_f32_e32 v88, v88
	v_mov_b32_e32 v150, v167
	v_pk_mul_f32 v[76:77], v[76:77], v[150:151] op_sel_hi:[1,0]
	v_rcp_f32_e32 v89, v89
	v_pk_mul_f32 v[78:79], v[78:79], v[150:151] op_sel_hi:[1,0]
	v_pk_mul_f32 v[72:73], v[72:73], v[150:151] op_sel_hi:[1,0]
	v_rcp_f32_e32 v90, v90
	v_pk_mul_f32 v[74:75], v[74:75], v[150:151] op_sel_hi:[1,0]
	v_rcp_f32_e32 v91, v91
	v_exp_f32_e32 v76, v76
	s_mov_b32 s8, 0x2c000
	v_fma_f32 v76, v76, v166, v166
	v_exp_f32_e32 v77, v77
	v_pk_mul_f32 v[84:85], v[84:85], v[92:93]
	v_fma_f32 v77, v77, v166, v166
	v_exp_f32_e32 v78, v78
	v_pk_mul_f32 v[86:87], v[86:87], v[94:95]
	v_fma_f32 v78, v78, v166, v166
	v_exp_f32_e32 v79, v79
	v_pk_mul_f32 v[80:81], v[80:81], v[88:89]
	v_fma_f32 v79, v79, v166, v166
	v_exp_f32_e32 v72, v72
	v_pk_mul_f32 v[82:83], v[82:83], v[90:91]
	v_fma_f32 v72, v72, v166, v166
	v_exp_f32_e32 v73, v73
	v_cvt_pk_bf16_f32 v92, v84, v85
	v_fma_f32 v73, v73, v166, v166
	v_exp_f32_e32 v74, v74
	v_cvt_pk_bf16_f32 v93, v86, v87
	v_fma_f32 v74, v74, v166, v166
	v_exp_f32_e32 v75, v75
	v_cvt_pk_bf16_f32 v94, v80, v81
	v_fma_f32 v75, v75, v166, v166
	v_rcp_f32_e32 v76, v76
	v_cvt_pk_bf16_f32 v95, v82, v83
	v_lshl_add_u64 v[178:179], v[176:177], 0, s[8:9]
	v_rcp_f32_e32 v77, v77
	global_store_dwordx4 v[178:179], v[92:95], off
	v_pk_mul_f32 v[52:53], v[60:61], v[52:53]
	v_rcp_f32_e32 v78, v78
	v_pk_mul_f32 v[54:55], v[62:63], v[54:55]
	v_pk_mul_f32 v[48:49], v[56:57], v[48:49]
	v_rcp_f32_e32 v79, v79
	v_pk_mul_f32 v[50:51], v[58:59], v[50:51]
	s_waitcnt lgkmcnt(3)
	v_rcp_f32_e32 v72, v72
	v_mov_b32_e32 v150, v169
	v_pk_mul_f32 v[60:61], v[60:61], v[150:151] op_sel_hi:[1,0]
	v_rcp_f32_e32 v73, v73
	v_pk_mul_f32 v[62:63], v[62:63], v[150:151] op_sel_hi:[1,0]
	v_pk_mul_f32 v[56:57], v[56:57], v[150:151] op_sel_hi:[1,0]
	v_rcp_f32_e32 v74, v74
	v_pk_mul_f32 v[58:59], v[58:59], v[150:151] op_sel_hi:[1,0]
	v_rcp_f32_e32 v75, v75
	v_exp_f32_e32 v60, v60
	s_mov_b32 s8, 0x42000
	v_fma_f32 v60, v60, v168, v168
	v_exp_f32_e32 v61, v61
	v_pk_mul_f32 v[68:69], v[68:69], v[76:77]
	v_fma_f32 v61, v61, v168, v168
	v_exp_f32_e32 v62, v62
	v_pk_mul_f32 v[70:71], v[70:71], v[78:79]
	v_fma_f32 v62, v62, v168, v168
	v_exp_f32_e32 v63, v63
	v_pk_mul_f32 v[64:65], v[64:65], v[72:73]
	v_fma_f32 v63, v63, v168, v168
	v_exp_f32_e32 v56, v56
	v_pk_mul_f32 v[66:67], v[66:67], v[74:75]
	v_fma_f32 v56, v56, v168, v168
	v_exp_f32_e32 v57, v57
	v_cvt_pk_bf16_f32 v76, v68, v69
	v_fma_f32 v57, v57, v168, v168
	v_exp_f32_e32 v58, v58
	v_cvt_pk_bf16_f32 v77, v70, v71
	v_fma_f32 v58, v58, v168, v168
	v_exp_f32_e32 v59, v59
	v_cvt_pk_bf16_f32 v78, v64, v65
	v_fma_f32 v59, v59, v168, v168
	v_rcp_f32_e32 v60, v60
	v_cvt_pk_bf16_f32 v79, v66, v67
	v_lshl_add_u64 v[178:179], v[176:177], 0, s[8:9]
	v_rcp_f32_e32 v61, v61
	global_store_dwordx4 v[178:179], v[76:79], off
	v_pk_mul_f32 v[36:37], v[44:45], v[36:37]
	v_rcp_f32_e32 v62, v62
	v_pk_mul_f32 v[38:39], v[46:47], v[38:39]
	v_pk_mul_f32 v[32:33], v[40:41], v[32:33]
	v_rcp_f32_e32 v63, v63
	v_pk_mul_f32 v[34:35], v[42:43], v[34:35]
	s_waitcnt lgkmcnt(2)
	v_rcp_f32_e32 v56, v56
	v_mov_b32_e32 v150, v171
	v_pk_mul_f32 v[44:45], v[44:45], v[150:151] op_sel_hi:[1,0]
	v_rcp_f32_e32 v57, v57
	v_pk_mul_f32 v[46:47], v[46:47], v[150:151] op_sel_hi:[1,0]
	v_pk_mul_f32 v[40:41], v[40:41], v[150:151] op_sel_hi:[1,0]
	v_rcp_f32_e32 v58, v58
	v_pk_mul_f32 v[42:43], v[42:43], v[150:151] op_sel_hi:[1,0]
	v_rcp_f32_e32 v59, v59
	v_exp_f32_e32 v44, v44
	s_mov_b32 s8, 0xb0000
	v_fma_f32 v44, v44, v170, v170
	v_exp_f32_e32 v45, v45
	v_pk_mul_f32 v[52:53], v[52:53], v[60:61]
	v_fma_f32 v45, v45, v170, v170
	v_exp_f32_e32 v46, v46
	v_pk_mul_f32 v[54:55], v[54:55], v[62:63]
	v_fma_f32 v46, v46, v170, v170
	v_exp_f32_e32 v47, v47
	v_pk_mul_f32 v[48:49], v[48:49], v[56:57]
	v_fma_f32 v47, v47, v170, v170
	v_exp_f32_e32 v40, v40
	v_pk_mul_f32 v[50:51], v[50:51], v[58:59]
	v_fma_f32 v40, v40, v170, v170
	v_exp_f32_e32 v41, v41
	v_cvt_pk_bf16_f32 v60, v52, v53
	v_fma_f32 v41, v41, v170, v170
	v_exp_f32_e32 v42, v42
	v_cvt_pk_bf16_f32 v61, v54, v55
	v_fma_f32 v42, v42, v170, v170
	v_exp_f32_e32 v43, v43
	v_cvt_pk_bf16_f32 v62, v48, v49
	v_fma_f32 v43, v43, v170, v170
	v_rcp_f32_e32 v44, v44
	v_cvt_pk_bf16_f32 v63, v50, v51
	v_lshl_add_u64 v[178:179], v[176:177], 0, s[8:9]
	v_rcp_f32_e32 v45, v45
	global_store_dwordx4 v[178:179], v[60:63], off
	v_pk_mul_f32 v[20:21], v[28:29], v[20:21]
	v_rcp_f32_e32 v46, v46
	v_pk_mul_f32 v[22:23], v[30:31], v[22:23]
	v_pk_mul_f32 v[16:17], v[24:25], v[16:17]
	v_rcp_f32_e32 v47, v47
	v_pk_mul_f32 v[18:19], v[26:27], v[18:19]
	s_waitcnt lgkmcnt(1)
; __device__ __forceinline__ unsigned cvtpk(float lo, float hi) { f32x2_t v = {lo, hi}; bf16x2_t b = __builtin_convertvector(v, bf16x2_t); return __builtin_bit_cast(unsigned, b); }
; #define PG8_BAR __builtin_amdgcn_s_barrier()
; template <class Epi>
; __device__ __forceinline__ void gemm_phase(LAS unsigned char* lds, const Gemm g, const StaticOrder& S, const Epi& E, int wave_s) {
;     ...
;         if (!has_next) break;
; #pragma unroll
;         for (int a = 0; a < 2; ++a)
; #pragma unroll
;             for (int b = 0; b < 2; ++b)
; #pragma unroll
;                 for (int m = 0; m < 4; ++m)
; #pragma unroll
;                     for (int n = 0; n < 2; ++n) acc[a][b][m][n] = (f32x4){0.f, 0.f, 0.f, 0.f};
;         cur = nxt; cA = nA; cB = nB; ++ui;
;         if (wr == 1) PG8_BAR;
;     __device__ __forceinline__ void operator()(const f32x4 (&acc)[2][2][4][2], const Unit& u, int wr, int wc, int fr, int fq) const {
;     ...
;             for (int m = 0; m < 4; ++m) {
;                 const int row = row0 + ai * HALF + m * 16;
;                 const float rs = 1.0f / sqrtf(ssq_sum(ssq + (size_t)row * 16) * (1.0f / DM) + EPS);
;                 float hv[8];
; #pragma unroll
;                 for (int n = 0; n < 2; ++n)
; #pragma unroll
;                     for (int e = 0; e < 4; ++e) {
;                         const float gg = acc[ai][0][m][n][e] * rs, uu = acc[ai][1][m][n][e] * rs;
;                         const float den = 1.0f + __builtin_amdgcn_exp2f(-gg * LOG2E);
;                         hv[n * 4 + e] = gg * uu * __builtin_amdgcn_rcpf(den);
;                     }
;                 u32x4 w; w.x = cvtpk(hv[0], hv[1]); w.y = cvtpk(hv[2], hv[3]); w.z = cvtpk(hv[4], hv[5]); w.w = cvtpk(hv[6], hv[7]);
;                 *(u32x4*)(H + (size_t)row * DFF + col0) = w;
	v_rcp_f32_e32 v40, v40
	v_mov_b32_e32 v150, v173
	v_pk_mul_f32 v[28:29], v[28:29], v[150:151] op_sel_hi:[1,0]
	v_rcp_f32_e32 v41, v41
	v_pk_mul_f32 v[30:31], v[30:31], v[150:151] op_sel_hi:[1,0]
	v_pk_mul_f32 v[24:25], v[24:25], v[150:151] op_sel_hi:[1,0]
	v_rcp_f32_e32 v42, v42
	v_pk_mul_f32 v[26:27], v[26:27], v[150:151] op_sel_hi:[1,0]
	v_rcp_f32_e32 v43, v43
	v_exp_f32_e32 v28, v28
	s_mov_b32 s8, 0xc6000
	v_fma_f32 v28, v28, v172, v172
	v_exp_f32_e32 v29, v29
	v_pk_mul_f32 v[36:37], v[36:37], v[44:45]
	v_fma_f32 v29, v29, v172, v172
	v_exp_f32_e32 v30, v30
	v_pk_mul_f32 v[38:39], v[38:39], v[46:47]
	v_fma_f32 v30, v30, v172, v172
	v_exp_f32_e32 v31, v31
	v_pk_mul_f32 v[32:33], v[32:33], v[40:41]
	v_fma_f32 v31, v31, v172, v172
	v_exp_f32_e32 v24, v24
	v_pk_mul_f32 v[34:35], v[34:35], v[42:43]
	v_fma_f32 v24, v24, v172, v172
	v_exp_f32_e32 v25, v25
	v_cvt_pk_bf16_f32 v44, v36, v37
	v_fma_f32 v25, v25, v172, v172
	v_exp_f32_e32 v26, v26
	v_cvt_pk_bf16_f32 v45, v38, v39
	v_fma_f32 v26, v26, v172, v172
	v_exp_f32_e32 v27, v27
	v_cvt_pk_bf16_f32 v46, v32, v33
	v_fma_f32 v27, v27, v172, v172
	v_rcp_f32_e32 v28, v28
	v_cvt_pk_bf16_f32 v47, v34, v35
	v_lshl_add_u64 v[178:179], v[176:177], 0, s[8:9]
	v_rcp_f32_e32 v29, v29
	global_store_dwordx4 v[178:179], v[44:47], off
	v_pk_mul_f32 v[4:5], v[12:13], v[4:5]
	v_rcp_f32_e32 v30, v30
	v_pk_mul_f32 v[6:7], v[14:15], v[6:7]
	v_pk_mul_f32 v[0:1], v[8:9], v[0:1]
	v_rcp_f32_e32 v31, v31
	v_pk_mul_f32 v[2:3], v[10:11], v[2:3]
	s_waitcnt lgkmcnt(0)
	v_rcp_f32_e32 v24, v24
	v_mov_b32_e32 v150, v175
	v_pk_mul_f32 v[12:13], v[12:13], v[150:151] op_sel_hi:[1,0]
	v_rcp_f32_e32 v25, v25
	v_pk_mul_f32 v[14:15], v[14:15], v[150:151] op_sel_hi:[1,0]
	v_pk_mul_f32 v[8:9], v[8:9], v[150:151] op_sel_hi:[1,0]
	v_rcp_f32_e32 v26, v26
	v_pk_mul_f32 v[10:11], v[10:11], v[150:151] op_sel_hi:[1,0]
	v_rcp_f32_e32 v27, v27
	v_exp_f32_e32 v12, v12
	s_mov_b32 s8, 0xdc000
	v_fma_f32 v12, v12, v174, v174
	v_exp_f32_e32 v13, v13
	v_pk_mul_f32 v[20:21], v[20:21], v[28:29]
	v_fma_f32 v13, v13, v174, v174
	v_exp_f32_e32 v14, v14
	v_pk_mul_f32 v[22:23], v[22:23], v[30:31]
	v_fma_f32 v14, v14, v174, v174
	v_exp_f32_e32 v15, v15
	v_pk_mul_f32 v[16:17], v[16:17], v[24:25]
	v_fma_f32 v15, v15, v174, v174
	v_exp_f32_e32 v8, v8
	v_pk_mul_f32 v[18:19], v[18:19], v[26:27]
	v_fma_f32 v8, v8, v174, v174
	v_exp_f32_e32 v9, v9
	v_cvt_pk_bf16_f32 v28, v20, v21
	v_fma_f32 v9, v9, v174, v174
	v_exp_f32_e32 v10, v10
	v_cvt_pk_bf16_f32 v29, v22, v23
	v_fma_f32 v10, v10, v174, v174
	v_exp_f32_e32 v11, v11
	v_cvt_pk_bf16_f32 v30, v16, v17
	v_fma_f32 v11, v11, v174, v174
	v_rcp_f32_e32 v12, v12
	v_cvt_pk_bf16_f32 v31, v18, v19
	v_lshl_add_u64 v[178:179], v[176:177], 0, s[8:9]
	v_rcp_f32_e32 v13, v13
	global_store_dwordx4 v[178:179], v[28:31], off
	v_rcp_f32_e32 v14, v14
	v_rcp_f32_e32 v15, v15
	v_rcp_f32_e32 v8, v8
	v_rcp_f32_e32 v9, v9
	v_rcp_f32_e32 v10, v10
	v_rcp_f32_e32 v11, v11
	s_mov_b32 s8, 0xf2000
	v_pk_mul_f32 v[4:5], v[4:5], v[12:13]
	v_pk_mul_f32 v[6:7], v[6:7], v[14:15]
	v_pk_mul_f32 v[0:1], v[0:1], v[8:9]
	v_pk_mul_f32 v[2:3], v[2:3], v[10:11]
	v_cvt_pk_bf16_f32 v12, v4, v5
	v_cvt_pk_bf16_f32 v13, v6, v7
	v_cvt_pk_bf16_f32 v14, v0, v1
	v_cvt_pk_bf16_f32 v15, v2, v3
	v_lshl_add_u64 v[178:179], v[176:177], 0, s[8:9]
	global_store_dwordx4 v[178:179], v[12:15], off
	s_andn2_b64 vcc, exec, s[6:7]
	s_mov_b64 s[6:7], -1
	s_cbranch_vccnz .LBB0_237
	s_andn2_b64 vcc, exec, s[12:13]
	s_cbranch_vccnz .LBB0_236
	s_barrier
	s_branch .LBB0_236

; __device__ __forceinline__ unsigned cvtpk(float lo, float hi) { f32x2_t v = {lo, hi}; bf16x2_t b = __builtin_convertvector(v, bf16x2_t); return __builtin_bit_cast(unsigned, b); }
;     __device__ __forceinline__ void operator()(const f32x4 (&acc)[2][2][4][2], const Unit& u, int wr, int wc, int fr, int fq) const {
;         const int row0 = u.pm * BM + wr * 64 + fr, col0 = u.pn * 128 + wc * 32 + 8 * fq;
; #pragma unroll
;         for (int ai = 0; ai < 2; ++ai)
; #pragma unroll
;             for (int m = 0; m < 4; ++m) {
;                 const int row = row0 + ai * HALF + m * 16;
;                 const float rs = 1.0f / sqrtf(ssq_sum(ssq + (size_t)row * 16) * (1.0f / DM) + EPS);
;                 float hv[8];
; #pragma unroll
;                 for (int n = 0; n < 2; ++n)
; #pragma unroll
;                     for (int e = 0; e < 4; ++e) {
;                         const float gg = acc[ai][0][m][n][e] * rs, uu = acc[ai][1][m][n][e] * rs;
;                         const float den = 1.0f + __builtin_amdgcn_exp2f(-gg * LOG2E);
;                         hv[n * 4 + e] = gg * uu * __builtin_amdgcn_rcpf(den);
;                     }
;                 u32x4 w; w.x = cvtpk(hv[0], hv[1]); w.y = cvtpk(hv[2], hv[3]); w.z = cvtpk(hv[4], hv[5]); w.w = cvtpk(hv[6], hv[7]);
;                 *(u32x4*)(H + (size_t)row * DFF + col0) = w;
;             }
.LBB0_1054:
	v_readlane_b32 s9, v254, 7
	v_mbcnt_lo_u32_b32 v144, -1, 0
	v_mbcnt_hi_u32_b32 v144, -1, v144
	v_lshrrev_b32_e32 v145, 1, v144
	v_lshl_add_u32 v145, s9, 5, v145
	v_and_b32_e32 v146, 1, v144
	v_lshl_add_u32 v147, s8, 8, v145
	v_lshlrev_b32_e32 v147, 6, v147
	v_lshl_add_u32 v147, v146, 5, v147
	global_load_dwordx4 v[160:163], v147, s[16:17]
	global_load_dwordx4 v[164:167], v147, s[16:17] offset:16
	v_lshl_add_u32 v148, s8, 8, v152
	v_mov_b64_e32 v[146:147], s[14:15]
	v_mad_i64_i32 v[176:177], s[8:9], v148, s51, v[146:147]
	v_lshl_or_b32 v150, s2, 7, v154
	v_mov_b32_e32 v151, 0
	v_lshlrev_b64 v[150:151], 1, v[150:151]
	v_lshl_add_u64 v[176:177], v[176:177], 0, v[150:151]
	v_lshlrev_b32_e32 v145, 3, v145
	v_add_u32_e32 v145, 0x20100, v145
	v_lshlrev_b32_e32 v146, 3, v152
	v_add_u32_e32 v146, 0x20100, v146
	s_mov_b32 s9, 0
	s_waitcnt vmcnt(0)
	v_pk_add_f32 v[160:161], v[160:161], v[162:163]
	v_pk_add_f32 v[164:165], v[164:165], v[166:167]
	v_pk_add_f32 v[160:161], v[160:161], v[164:165]
	v_add_f32_e32 v160, v160, v161
	s_nop 1
	v_add_f32_dpp v160, v160, v160 quad_perm:[1,0,3,2] row_mask:0xf bank_mask:0xf
	v_fmamk_f32 v160, v160, 0x3a800000, v158
	v_rsq_f32_e32 v161, v160
	s_nop 0
	v_mul_f32_e32 v161, 0xbfb8aa3b, v161
	ds_write_b64 v145, v[160:161]
	s_waitcnt lgkmcnt(0)
	s_barrier
	ds_read_b64 v[160:161], v146 offset:0
	ds_read_b64 v[162:163], v146 offset:128
	ds_read_b64 v[164:165], v146 offset:256
	ds_read_b64 v[166:167], v146 offset:384
	ds_read_b64 v[168:169], v146 offset:1024
	ds_read_b64 v[170:171], v146 offset:1152
	ds_read_b64 v[172:173], v146 offset:1280
	ds_read_b64 v[174:175], v146 offset:1408
	v_pk_mul_f32 v[116:117], v[124:125], v[116:117]
	v_pk_mul_f32 v[118:119], v[126:127], v[118:119]
	v_pk_mul_f32 v[112:113], v[120:121], v[112:113]
	v_pk_mul_f32 v[114:115], v[122:123], v[114:115]
	s_waitcnt lgkmcnt(7)
	v_mov_b32_e32 v150, v161
	v_pk_mul_f32 v[124:125], v[124:125], v[150:151] op_sel_hi:[1,0]
	v_pk_mul_f32 v[126:127], v[126:127], v[150:151] op_sel_hi:[1,0]
	v_pk_mul_f32 v[120:121], v[120:121], v[150:151] op_sel_hi:[1,0]
	v_pk_mul_f32 v[122:123], v[122:123], v[150:151] op_sel_hi:[1,0]
	v_exp_f32_e32 v124, v124
	v_pk_mul_f32 v[100:101], v[108:109], v[100:101]
	v_fma_f32 v124, v124, v160, v160
	v_exp_f32_e32 v125, v125
	v_pk_mul_f32 v[102:103], v[110:111], v[102:103]
	v_fma_f32 v125, v125, v160, v160
	v_exp_f32_e32 v126, v126
	v_pk_mul_f32 v[96:97], v[104:105], v[96:97]
	v_fma_f32 v126, v126, v160, v160
	v_exp_f32_e32 v127, v127
	v_pk_mul_f32 v[98:99], v[106:107], v[98:99]
	v_fma_f32 v127, v127, v160, v160
	v_exp_f32_e32 v120, v120
	s_waitcnt lgkmcnt(6)
	v_fma_f32 v120, v120, v160, v160
	v_exp_f32_e32 v121, v121
	v_mov_b32_e32 v150, v163
	v_fma_f32 v121, v121, v160, v160
	v_exp_f32_e32 v122, v122
	v_pk_mul_f32 v[108:109], v[108:109], v[150:151] op_sel_hi:[1,0]
	v_fma_f32 v122, v122, v160, v160
	v_exp_f32_e32 v123, v123
	v_pk_mul_f32 v[110:111], v[110:111], v[150:151] op_sel_hi:[1,0]
	v_fma_f32 v123, v123, v160, v160
	v_rcp_f32_e32 v124, v124
	v_pk_mul_f32 v[104:105], v[104:105], v[150:151] op_sel_hi:[1,0]
	v_pk_mul_f32 v[106:107], v[106:107], v[150:151] op_sel_hi:[1,0]
	v_rcp_f32_e32 v125, v125
	v_rcp_f32_e32 v126, v126
	v_rcp_f32_e32 v127, v127
	v_rcp_f32_e32 v120, v120
	v_rcp_f32_e32 v121, v121
	v_rcp_f32_e32 v122, v122
	v_rcp_f32_e32 v123, v123
	v_exp_f32_e32 v108, v108
	v_pk_mul_f32 v[116:117], v[116:117], v[124:125]
	v_fma_f32 v108, v108, v162, v162
	v_exp_f32_e32 v109, v109
	v_pk_mul_f32 v[118:119], v[118:119], v[126:127]
	v_fma_f32 v109, v109, v162, v162
	v_exp_f32_e32 v110, v110
	v_pk_mul_f32 v[112:113], v[112:113], v[120:121]
	v_fma_f32 v110, v110, v162, v162
	v_exp_f32_e32 v111, v111
	v_pk_mul_f32 v[114:115], v[114:115], v[122:123]
	v_fma_f32 v111, v111, v162, v162
	v_exp_f32_e32 v104, v104
	v_cvt_pk_bf16_f32 v124, v116, v117
	v_fma_f32 v104, v104, v162, v162
	v_exp_f32_e32 v105, v105
	v_cvt_pk_bf16_f32 v125, v118, v119
	v_fma_f32 v105, v105, v162, v162
	v_exp_f32_e32 v106, v106
	v_cvt_pk_bf16_f32 v126, v112, v113
	v_fma_f32 v106, v106, v162, v162
	v_exp_f32_e32 v107, v107
	v_cvt_pk_bf16_f32 v127, v114, v115
	v_fma_f32 v107, v107, v162, v162
	v_rcp_f32_e32 v108, v108
	global_store_dwordx4 v[176:177], v[124:127], off
	v_pk_mul_f32 v[84:85], v[92:93], v[84:85]
	v_rcp_f32_e32 v109, v109
	v_pk_mul_f32 v[86:87], v[94:95], v[86:87]
	v_pk_mul_f32 v[80:81], v[88:89], v[80:81]
	v_rcp_f32_e32 v110, v110
	v_pk_mul_f32 v[82:83], v[90:91], v[82:83]
	s_waitcnt lgkmcnt(5)
	v_rcp_f32_e32 v111, v111
	v_mov_b32_e32 v150, v165
	v_pk_mul_f32 v[92:93], v[92:93], v[150:151] op_sel_hi:[1,0]
	v_rcp_f32_e32 v104, v104
	v_pk_mul_f32 v[94:95], v[94:95], v[150:151] op_sel_hi:[1,0]
	v_pk_mul_f32 v[88:89], v[88:89], v[150:151] op_sel_hi:[1,0]
	v_rcp_f32_e32 v105, v105
	v_pk_mul_f32 v[90:91], v[90:91], v[150:151] op_sel_hi:[1,0]
	v_rcp_f32_e32 v106, v106
	v_rcp_f32_e32 v107, v107
	v_exp_f32_e32 v92, v92
	s_mov_b32 s8, 0x16000
	v_fma_f32 v92, v92, v164, v164
	v_exp_f32_e32 v93, v93
	v_pk_mul_f32 v[100:101], v[100:101], v[108:109]
	v_fma_f32 v93, v93, v164, v164
	v_exp_f32_e32 v94, v94
	v_pk_mul_f32 v[102:103], v[102:103], v[110:111]
	v_fma_f32 v94, v94, v164, v164
	v_exp_f32_e32 v95, v95
	v_pk_mul_f32 v[96:97], v[96:97], v[104:105]
	v_fma_f32 v95, v95, v164, v164
	v_exp_f32_e32 v88, v88
	v_pk_mul_f32 v[98:99], v[98:99], v[106:107]
	v_fma_f32 v88, v88, v164, v164
	v_exp_f32_e32 v89, v89
	v_cvt_pk_bf16_f32 v108, v100, v101
	v_fma_f32 v89, v89, v164, v164
	v_exp_f32_e32 v90, v90
	v_cvt_pk_bf16_f32 v109, v102, v103
	v_fma_f32 v90, v90, v164, v164
	v_exp_f32_e32 v91, v91
	v_cvt_pk_bf16_f32 v110, v96, v97
	v_fma_f32 v91, v91, v164, v164
	v_rcp_f32_e32 v92, v92
	v_cvt_pk_bf16_f32 v111, v98, v99
	v_lshl_add_u64 v[178:179], v[176:177], 0, s[8:9]
	v_rcp_f32_e32 v93, v93
	global_store_dwordx4 v[178:179], v[108:111], off
	v_pk_mul_f32 v[68:69], v[76:77], v[68:69]
	v_rcp_f32_e32 v94, v94
	v_pk_mul_f32 v[70:71], v[78:79], v[70:71]
	v_pk_mul_f32 v[64:65], v[72:73], v[64:65]
	v_rcp_f32_e32 v95, v95
	v_pk_mul_f32 v[66:67], v[74:75], v[66:67]
	s_waitcnt lgkmcnt(4)
; __device__ __forceinline__ unsigned cvtpk(float lo, float hi) { f32x2_t v = {lo, hi}; bf16x2_t b = __builtin_convertvector(v, bf16x2_t); return __builtin_bit_cast(unsigned, b); }
;     __device__ __forceinline__ void operator()(const f32x4 (&acc)[2][2][4][2], const Unit& u, int wr, int wc, int fr, int fq) const {
;     ...
;             for (int m = 0; m < 4; ++m) {
;                 const int row = row0 + ai * HALF + m * 16;
;                 const float rs = 1.0f / sqrtf(ssq_sum(ssq + (size_t)row * 16) * (1.0f / DM) + EPS);
;                 float hv[8];
; #pragma unroll
;                 for (int n = 0; n < 2; ++n)
; #pragma unroll
;                     for (int e = 0; e < 4; ++e) {
;                         const float gg = acc[ai][0][m][n][e] * rs, uu = acc[ai][1][m][n][e] * rs;
;                         const float den = 1.0f + __builtin_amdgcn_exp2f(-gg * LOG2E);
;                         hv[n * 4 + e] = gg * uu * __builtin_amdgcn_rcpf(den);
;                     }
;                 u32x4 w; w.x = cvtpk(hv[0], hv[1]); w.y = cvtpk(hv[2], hv[3]); w.z = cvtpk(hv[4], hv[5]); w.w = cvtpk(hv[6], hv[7]);
;                 *(u32x4*)(H + (size_t)row * DFF + col0) = w;
	v_rcp_f32_e32 v88, v88
	v_mov_b32_e32 v150, v167
	v_pk_mul_f32 v[76:77], v[76:77], v[150:151] op_sel_hi:[1,0]
	v_rcp_f32_e32 v89, v89
	v_pk_mul_f32 v[78:79], v[78:79], v[150:151] op_sel_hi:[1,0]
	v_pk_mul_f32 v[72:73], v[72:73], v[150:151] op_sel_hi:[1,0]
	v_rcp_f32_e32 v90, v90
	v_pk_mul_f32 v[74:75], v[74:75], v[150:151] op_sel_hi:[1,0]
	v_rcp_f32_e32 v91, v91
	v_exp_f32_e32 v76, v76
	s_mov_b32 s8, 0x2c000
	v_fma_f32 v76, v76, v166, v166
	v_exp_f32_e32 v77, v77
	v_pk_mul_f32 v[84:85], v[84:85], v[92:93]
	v_fma_f32 v77, v77, v166, v166
	v_exp_f32_e32 v78, v78
	v_pk_mul_f32 v[86:87], v[86:87], v[94:95]
	v_fma_f32 v78, v78, v166, v166
	v_exp_f32_e32 v79, v79
	v_pk_mul_f32 v[80:81], v[80:81], v[88:89]
	v_fma_f32 v79, v79, v166, v166
	v_exp_f32_e32 v72, v72
	v_pk_mul_f32 v[82:83], v[82:83], v[90:91]
	v_fma_f32 v72, v72, v166, v166
	v_exp_f32_e32 v73, v73
	v_cvt_pk_bf16_f32 v92, v84, v85
	v_fma_f32 v73, v73, v166, v166
	v_exp_f32_e32 v74, v74
	v_cvt_pk_bf16_f32 v93, v86, v87
	v_fma_f32 v74, v74, v166, v166
	v_exp_f32_e32 v75, v75
	v_cvt_pk_bf16_f32 v94, v80, v81
	v_fma_f32 v75, v75, v166, v166
	v_rcp_f32_e32 v76, v76
	v_cvt_pk_bf16_f32 v95, v82, v83
	v_lshl_add_u64 v[178:179], v[176:177], 0, s[8:9]
	v_rcp_f32_e32 v77, v77
	global_store_dwordx4 v[178:179], v[92:95], off
	v_pk_mul_f32 v[52:53], v[60:61], v[52:53]
	v_rcp_f32_e32 v78, v78
	v_pk_mul_f32 v[54:55], v[62:63], v[54:55]
	v_pk_mul_f32 v[48:49], v[56:57], v[48:49]
	v_rcp_f32_e32 v79, v79
	v_pk_mul_f32 v[50:51], v[58:59], v[50:51]
	s_waitcnt lgkmcnt(3)
	v_rcp_f32_e32 v72, v72
	v_mov_b32_e32 v150, v169
	v_pk_mul_f32 v[60:61], v[60:61], v[150:151] op_sel_hi:[1,0]
	v_rcp_f32_e32 v73, v73
	v_pk_mul_f32 v[62:63], v[62:63], v[150:151] op_sel_hi:[1,0]
	v_pk_mul_f32 v[56:57], v[56:57], v[150:151] op_sel_hi:[1,0]
	v_rcp_f32_e32 v74, v74
	v_pk_mul_f32 v[58:59], v[58:59], v[150:151] op_sel_hi:[1,0]
	v_rcp_f32_e32 v75, v75
	v_exp_f32_e32 v60, v60
	s_mov_b32 s8, 0x42000
	v_fma_f32 v60, v60, v168, v168
	v_exp_f32_e32 v61, v61
	v_pk_mul_f32 v[68:69], v[68:69], v[76:77]
	v_fma_f32 v61, v61, v168, v168
	v_exp_f32_e32 v62, v62
	v_pk_mul_f32 v[70:71], v[70:71], v[78:79]
	v_fma_f32 v62, v62, v168, v168
	v_exp_f32_e32 v63, v63
	v_pk_mul_f32 v[64:65], v[64:65], v[72:73]
	v_fma_f32 v63, v63, v168, v168
	v_exp_f32_e32 v56, v56
	v_pk_mul_f32 v[66:67], v[66:67], v[74:75]
	v_fma_f32 v56, v56, v168, v168
	v_exp_f32_e32 v57, v57
	v_cvt_pk_bf16_f32 v76, v68, v69
	v_fma_f32 v57, v57, v168, v168
	v_exp_f32_e32 v58, v58
	v_cvt_pk_bf16_f32 v77, v70, v71
	v_fma_f32 v58, v58, v168, v168
	v_exp_f32_e32 v59, v59
	v_cvt_pk_bf16_f32 v78, v64, v65
	v_fma_f32 v59, v59, v168, v168
	v_rcp_f32_e32 v60, v60
	v_cvt_pk_bf16_f32 v79, v66, v67
	v_lshl_add_u64 v[178:179], v[176:177], 0, s[8:9]
	v_rcp_f32_e32 v61, v61
	global_store_dwordx4 v[178:179], v[76:79], off
	v_pk_mul_f32 v[36:37], v[44:45], v[36:37]
	v_rcp_f32_e32 v62, v62
	v_pk_mul_f32 v[38:39], v[46:47], v[38:39]
	v_pk_mul_f32 v[32:33], v[40:41], v[32:33]
	v_rcp_f32_e32 v63, v63
	v_pk_mul_f32 v[34:35], v[42:43], v[34:35]
	s_waitcnt lgkmcnt(2)
	v_rcp_f32_e32 v56, v56
	v_mov_b32_e32 v150, v171
	v_pk_mul_f32 v[44:45], v[44:45], v[150:151] op_sel_hi:[1,0]
	v_rcp_f32_e32 v57, v57
	v_pk_mul_f32 v[46:47], v[46:47], v[150:151] op_sel_hi:[1,0]
	v_pk_mul_f32 v[40:41], v[40:41], v[150:151] op_sel_hi:[1,0]
	v_rcp_f32_e32 v58, v58
	v_pk_mul_f32 v[42:43], v[42:43], v[150:151] op_sel_hi:[1,0]
	v_rcp_f32_e32 v59, v59
	v_exp_f32_e32 v44, v44
	s_mov_b32 s8, 0xb0000
	v_fma_f32 v44, v44, v170, v170
	v_exp_f32_e32 v45, v45
	v_pk_mul_f32 v[52:53], v[52:53], v[60:61]
	v_fma_f32 v45, v45, v170, v170
	v_exp_f32_e32 v46, v46
	v_pk_mul_f32 v[54:55], v[54:55], v[62:63]
	v_fma_f32 v46, v46, v170, v170
	v_exp_f32_e32 v47, v47
	v_pk_mul_f32 v[48:49], v[48:49], v[56:57]
	v_fma_f32 v47, v47, v170, v170
	v_exp_f32_e32 v40, v40
	v_pk_mul_f32 v[50:51], v[50:51], v[58:59]
	v_fma_f32 v40, v40, v170, v170
	v_exp_f32_e32 v41, v41
	v_cvt_pk_bf16_f32 v60, v52, v53
	v_fma_f32 v41, v41, v170, v170
	v_exp_f32_e32 v42, v42
	v_cvt_pk_bf16_f32 v61, v54, v55
	v_fma_f32 v42, v42, v170, v170
	v_exp_f32_e32 v43, v43
	v_cvt_pk_bf16_f32 v62, v48, v49
	v_fma_f32 v43, v43, v170, v170
	v_rcp_f32_e32 v44, v44
	v_cvt_pk_bf16_f32 v63, v50, v51
	v_lshl_add_u64 v[178:179], v[176:177], 0, s[8:9]
	v_rcp_f32_e32 v45, v45
	global_store_dwordx4 v[178:179], v[60:63], off
	v_pk_mul_f32 v[20:21], v[28:29], v[20:21]
	v_rcp_f32_e32 v46, v46
	v_pk_mul_f32 v[22:23], v[30:31], v[22:23]
	v_pk_mul_f32 v[16:17], v[24:25], v[16:17]
	v_rcp_f32_e32 v47, v47
	v_pk_mul_f32 v[18:19], v[26:27], v[18:19]
	s_waitcnt lgkmcnt(1)
; __device__ __forceinline__ unsigned cvtpk(float lo, float hi) { f32x2_t v = {lo, hi}; bf16x2_t b = __builtin_convertvector(v, bf16x2_t); return __builtin_bit_cast(unsigned, b); }
; #define PG8_BAR __builtin_amdgcn_s_barrier()
; template <class Epi>
; __device__ __forceinline__ void gemm_phase(LAS unsigned char* lds, const Gemm g, const StaticOrder& S, const Epi& E, int wave_s) {
;     ...
;         if (!has_next) break;
; #pragma unroll
;         for (int a = 0; a < 2; ++a)
; #pragma unroll
;             for (int b = 0; b < 2; ++b)
; #pragma unroll
;                 for (int m = 0; m < 4; ++m)
; #pragma unroll
;                     for (int n = 0; n < 2; ++n) acc[a][b][m][n] = (f32x4){0.f, 0.f, 0.f, 0.f};
;         cur = nxt; cA = nA; cB = nB; ++ui;
;         if (wr == 1) PG8_BAR;
;     __device__ __forceinline__ void operator()(const f32x4 (&acc)[2][2][4][2], const Unit& u, int wr, int wc, int fr, int fq) const {
;     ...
;             for (int m = 0; m < 4; ++m) {
;                 const int row = row0 + ai * HALF + m * 16;
;                 const float rs = 1.0f / sqrtf(ssq_sum(ssq + (size_t)row * 16) * (1.0f / DM) + EPS);
;                 float hv[8];
; #pragma unroll
;                 for (int n = 0; n < 2; ++n)
; #pragma unroll
;                     for (int e = 0; e < 4; ++e) {
;                         const float gg = acc[ai][0][m][n][e] * rs, uu = acc[ai][1][m][n][e] * rs;
;                         const float den = 1.0f + __builtin_amdgcn_exp2f(-gg * LOG2E);
;                         hv[n * 4 + e] = gg * uu * __builtin_amdgcn_rcpf(den);
;                     }
;                 u32x4 w; w.x = cvtpk(hv[0], hv[1]); w.y = cvtpk(hv[2], hv[3]); w.z = cvtpk(hv[4], hv[5]); w.w = cvtpk(hv[6], hv[7]);
;                 *(u32x4*)(H + (size_t)row * DFF + col0) = w;
	v_rcp_f32_e32 v40, v40
	v_mov_b32_e32 v150, v173
	v_pk_mul_f32 v[28:29], v[28:29], v[150:151] op_sel_hi:[1,0]
	v_rcp_f32_e32 v41, v41
	v_pk_mul_f32 v[30:31], v[30:31], v[150:151] op_sel_hi:[1,0]
	v_pk_mul_f32 v[24:25], v[24:25], v[150:151] op_sel_hi:[1,0]
	v_rcp_f32_e32 v42, v42
	v_pk_mul_f32 v[26:27], v[26:27], v[150:151] op_sel_hi:[1,0]
	v_rcp_f32_e32 v43, v43
	v_exp_f32_e32 v28, v28
	s_mov_b32 s8, 0xc6000
	v_fma_f32 v28, v28, v172, v172
	v_exp_f32_e32 v29, v29
	v_pk_mul_f32 v[36:37], v[36:37], v[44:45]
	v_fma_f32 v29, v29, v172, v172
	v_exp_f32_e32 v30, v30
	v_pk_mul_f32 v[38:39], v[38:39], v[46:47]
	v_fma_f32 v30, v30, v172, v172
	v_exp_f32_e32 v31, v31
	v_pk_mul_f32 v[32:33], v[32:33], v[40:41]
	v_fma_f32 v31, v31, v172, v172
	v_exp_f32_e32 v24, v24
	v_pk_mul_f32 v[34:35], v[34:35], v[42:43]
	v_fma_f32 v24, v24, v172, v172
	v_exp_f32_e32 v25, v25
	v_cvt_pk_bf16_f32 v44, v36, v37
	v_fma_f32 v25, v25, v172, v172
	v_exp_f32_e32 v26, v26
	v_cvt_pk_bf16_f32 v45, v38, v39
	v_fma_f32 v26, v26, v172, v172
	v_exp_f32_e32 v27, v27
	v_cvt_pk_bf16_f32 v46, v32, v33
	v_fma_f32 v27, v27, v172, v172
	v_rcp_f32_e32 v28, v28
	v_cvt_pk_bf16_f32 v47, v34, v35
	v_lshl_add_u64 v[178:179], v[176:177], 0, s[8:9]
	v_rcp_f32_e32 v29, v29
	global_store_dwordx4 v[178:179], v[44:47], off
	v_pk_mul_f32 v[4:5], v[12:13], v[4:5]
	v_rcp_f32_e32 v30, v30
	v_pk_mul_f32 v[6:7], v[14:15], v[6:7]
	v_pk_mul_f32 v[0:1], v[8:9], v[0:1]
	v_rcp_f32_e32 v31, v31
	v_pk_mul_f32 v[2:3], v[10:11], v[2:3]
	s_waitcnt lgkmcnt(0)
	v_rcp_f32_e32 v24, v24
	v_mov_b32_e32 v150, v175
	v_pk_mul_f32 v[12:13], v[12:13], v[150:151] op_sel_hi:[1,0]
	v_rcp_f32_e32 v25, v25
	v_pk_mul_f32 v[14:15], v[14:15], v[150:151] op_sel_hi:[1,0]
	v_pk_mul_f32 v[8:9], v[8:9], v[150:151] op_sel_hi:[1,0]
	v_rcp_f32_e32 v26, v26
	v_pk_mul_f32 v[10:11], v[10:11], v[150:151] op_sel_hi:[1,0]
	v_rcp_f32_e32 v27, v27
	v_exp_f32_e32 v12, v12
	s_mov_b32 s8, 0xdc000
	v_fma_f32 v12, v12, v174, v174
	v_exp_f32_e32 v13, v13
	v_pk_mul_f32 v[20:21], v[20:21], v[28:29]
	v_fma_f32 v13, v13, v174, v174
	v_exp_f32_e32 v14, v14
	v_pk_mul_f32 v[22:23], v[22:23], v[30:31]
	v_fma_f32 v14, v14, v174, v174
	v_exp_f32_e32 v15, v15
	v_pk_mul_f32 v[16:17], v[16:17], v[24:25]
	v_fma_f32 v15, v15, v174, v174
	v_exp_f32_e32 v8, v8
	v_pk_mul_f32 v[18:19], v[18:19], v[26:27]
	v_fma_f32 v8, v8, v174, v174
	v_exp_f32_e32 v9, v9
	v_cvt_pk_bf16_f32 v28, v20, v21
	v_fma_f32 v9, v9, v174, v174
	v_exp_f32_e32 v10, v10
	v_cvt_pk_bf16_f32 v29, v22, v23
	v_fma_f32 v10, v10, v174, v174
	v_exp_f32_e32 v11, v11
	v_cvt_pk_bf16_f32 v30, v16, v17
	v_fma_f32 v11, v11, v174, v174
	v_rcp_f32_e32 v12, v12
	v_cvt_pk_bf16_f32 v31, v18, v19
	v_lshl_add_u64 v[178:179], v[176:177], 0, s[8:9]
	v_rcp_f32_e32 v13, v13
	global_store_dwordx4 v[178:179], v[28:31], off
	v_rcp_f32_e32 v14, v14
	v_rcp_f32_e32 v15, v15
	v_rcp_f32_e32 v8, v8
	v_rcp_f32_e32 v9, v9
	v_rcp_f32_e32 v10, v10
	v_rcp_f32_e32 v11, v11
	s_mov_b32 s8, 0xf2000
	v_pk_mul_f32 v[4:5], v[4:5], v[12:13]
	v_pk_mul_f32 v[6:7], v[6:7], v[14:15]
	v_pk_mul_f32 v[0:1], v[0:1], v[8:9]
	v_pk_mul_f32 v[2:3], v[2:3], v[10:11]
	v_cvt_pk_bf16_f32 v12, v4, v5
	v_cvt_pk_bf16_f32 v13, v6, v7
	v_cvt_pk_bf16_f32 v14, v0, v1
	v_cvt_pk_bf16_f32 v15, v2, v3
	v_lshl_add_u64 v[178:179], v[176:177], 0, s[8:9]
	global_store_dwordx4 v[178:179], v[12:15], off
	s_andn2_b64 vcc, exec, s[6:7]
	s_mov_b64 s[6:7], -1
	s_cbranch_vccnz .LBB0_1047
	s_andn2_b64 vcc, exec, s[12:13]
	s_cbranch_vccnz .LBB0_1046
	s_barrier
	s_branch .LBB0_1046
